# P7 fused epilogue (out-proj: post-norm + residual + next pre-norm) also rewritten by hand like P9: residual loads before sumsq atomics/panel syncs, counted vmcnt row pipeline
# speedup vs baseline: 1.0046x; 1.0010x over previous
.LBB0_704:
	s_lshl_b32 s0, s10, 8
	s_add_i32 s0, s0, s42
	v_or_b32_e32 v211, s0, v150
	v_lshlrev_b32_e32 v214, 3, v1
	v_lshl_or_b32 v214, s11, 8, v214
	v_or_b32_e32 v214, s30, v214
	v_lshlrev_b32_e32 v210, 12, v211
	v_lshl_add_u32 v210, v214, 2, v210
	v_lshlrev_b32_e32 v215, 11, v211
	v_lshl_add_u32 v215, v214, 1, v215
	v_lshlrev_b32_e32 v211, 2, v211
	v_lshlrev_b32_e32 v214, 2, v214
	s_sub_u32 s40, s70, 0x2000000
	s_subb_u32 s41, s71, 0
	s_cmp_lt_i32 s10, 32
	s_cselect_b32 s40, s68, s40
	s_cselect_b32 s41, s69, s41
	s_add_u32 s36, s40, 0x0
	s_addc_u32 s37, s41, 0
	global_load_dwordx4 v[130:133], v210, s[36:37]
	global_load_dwordx4 v[134:137], v210, s[36:37] offset:16
	global_load_dwordx4 v[138:141], v210, s[36:37] offset:512
	global_load_dwordx4 v[142:145], v210, s[36:37] offset:528
	s_add_u32 s36, s40, 0x10000
	s_addc_u32 s37, s41, 0
	global_load_dwordx4 v[146:149], v210, s[36:37]
	global_load_dwordx4 v[150:153], v210, s[36:37] offset:16
	global_load_dwordx4 v[154:157], v210, s[36:37] offset:512
	global_load_dwordx4 v[158:161], v210, s[36:37] offset:528
	s_add_u32 s36, s40, 0x20000
	s_addc_u32 s37, s41, 0
	global_load_dwordx4 v[162:165], v210, s[36:37]
	global_load_dwordx4 v[166:169], v210, s[36:37] offset:16
	global_load_dwordx4 v[170:173], v210, s[36:37] offset:512
	global_load_dwordx4 v[174:177], v210, s[36:37] offset:528
	s_add_u32 s36, s40, 0x30000
	s_addc_u32 s37, s41, 0
	global_load_dwordx4 v[178:181], v210, s[36:37]
	global_load_dwordx4 v[182:185], v210, s[36:37] offset:16
	global_load_dwordx4 v[186:189], v210, s[36:37] offset:512
	global_load_dwordx4 v[190:193], v210, s[36:37] offset:528
	s_cmpk_gt_u32 s31, 0xff
	s_cbranch_scc1 .LBB0_706
	s_barrier
.LBB0_706:
	v_mbcnt_lo_u32_b32 v212, -1, 0
	v_mbcnt_hi_u32_b32 v212, -1, v212
	v_xor_b32_e32 v213, 32, v212
	v_xor_b32_e32 v212, 16, v212
	v_lshlrev_b32_e32 v213, 2, v213
	v_lshlrev_b32_e32 v212, 2, v212
	v_mul_f32_e32 v242, v126, v126
	v_mul_f32_e32 v243, v122, v122
	v_mul_f32_e32 v244, v118, v118
	v_mul_f32_e32 v245, v110, v110
	v_mul_f32_e32 v221, v114, v114
	v_mul_f32_e32 v222, v106, v106
	v_mul_f32_e32 v223, v102, v102
	v_mul_f32_e32 v224, v98, v98
	v_fmac_f32_e32 v242, v127, v127
	v_fmac_f32_e32 v243, v123, v123
	v_fmac_f32_e32 v244, v119, v119
	v_fmac_f32_e32 v245, v111, v111
	v_fmac_f32_e32 v221, v115, v115
	v_fmac_f32_e32 v222, v107, v107
	v_fmac_f32_e32 v223, v103, v103
	v_fmac_f32_e32 v224, v99, v99
	v_fmac_f32_e32 v242, v128, v128
	v_fmac_f32_e32 v243, v124, v124
	v_fmac_f32_e32 v244, v120, v120
	v_fmac_f32_e32 v245, v112, v112
	v_fmac_f32_e32 v221, v116, v116
	v_fmac_f32_e32 v222, v108, v108
	v_fmac_f32_e32 v223, v104, v104
	v_fmac_f32_e32 v224, v100, v100
	v_fmac_f32_e32 v242, v129, v129
	v_fmac_f32_e32 v243, v125, v125
	v_fmac_f32_e32 v244, v121, v121
	v_fmac_f32_e32 v245, v113, v113
	v_fmac_f32_e32 v221, v117, v117
	v_fmac_f32_e32 v222, v109, v109
	v_fmac_f32_e32 v223, v105, v105
	v_fmac_f32_e32 v224, v101, v101
	v_add_f32_e32 v242, v242, v243
	v_add_f32_e32 v244, v244, v245
	v_add_f32_e32 v247, v242, v244
	v_add_f32_e32 v221, v221, v222
	v_add_f32_e32 v223, v223, v224
	v_add_f32_e32 v248, v221, v223
	v_mul_f32_e32 v242, v94, v94
	v_mul_f32_e32 v243, v90, v90
	v_mul_f32_e32 v244, v86, v86
	v_mul_f32_e32 v245, v82, v82
	v_mul_f32_e32 v221, v78, v78
	v_mul_f32_e32 v222, v74, v74
	v_mul_f32_e32 v223, v70, v70
	v_mul_f32_e32 v224, v66, v66
	v_fmac_f32_e32 v242, v95, v95
	v_fmac_f32_e32 v243, v91, v91
	v_fmac_f32_e32 v244, v87, v87
	v_fmac_f32_e32 v245, v83, v83
	v_fmac_f32_e32 v221, v79, v79
	v_fmac_f32_e32 v222, v75, v75
	v_fmac_f32_e32 v223, v71, v71
	v_fmac_f32_e32 v224, v67, v67
	v_fmac_f32_e32 v242, v96, v96
	v_fmac_f32_e32 v243, v92, v92
	v_fmac_f32_e32 v244, v88, v88
	v_fmac_f32_e32 v245, v84, v84
	v_fmac_f32_e32 v221, v80, v80
	v_fmac_f32_e32 v222, v76, v76
	v_fmac_f32_e32 v223, v72, v72
	v_fmac_f32_e32 v224, v68, v68
	v_fmac_f32_e32 v242, v97, v97
	v_fmac_f32_e32 v243, v93, v93
	v_fmac_f32_e32 v244, v89, v89
	v_fmac_f32_e32 v245, v85, v85
	v_fmac_f32_e32 v221, v81, v81
	v_fmac_f32_e32 v222, v77, v77
	v_fmac_f32_e32 v223, v73, v73
	v_fmac_f32_e32 v224, v69, v69
	v_add_f32_e32 v242, v242, v243
	v_add_f32_e32 v244, v244, v245
	v_add_f32_e32 v249, v242, v244
	v_add_f32_e32 v221, v221, v222
	v_add_f32_e32 v223, v223, v224
	v_add_f32_e32 v250, v221, v223
	v_mul_f32_e32 v242, v62, v62
	v_mul_f32_e32 v243, v58, v58
	v_mul_f32_e32 v244, v54, v54
	v_mul_f32_e32 v245, v50, v50
	v_mul_f32_e32 v221, v46, v46
	v_mul_f32_e32 v222, v42, v42
	v_mul_f32_e32 v223, v38, v38
	v_mul_f32_e32 v224, v34, v34
	v_fmac_f32_e32 v242, v63, v63
	v_fmac_f32_e32 v243, v59, v59
	v_fmac_f32_e32 v244, v55, v55
	v_fmac_f32_e32 v245, v51, v51
	v_fmac_f32_e32 v221, v47, v47
	v_fmac_f32_e32 v222, v43, v43
	v_fmac_f32_e32 v223, v39, v39
	v_fmac_f32_e32 v224, v35, v35
	v_fmac_f32_e32 v242, v64, v64
	v_fmac_f32_e32 v243, v60, v60
	v_fmac_f32_e32 v244, v56, v56
	v_fmac_f32_e32 v245, v52, v52
	v_fmac_f32_e32 v221, v48, v48
	v_fmac_f32_e32 v222, v44, v44
	v_fmac_f32_e32 v223, v40, v40
	v_fmac_f32_e32 v224, v36, v36
	v_fmac_f32_e32 v242, v65, v65
	v_fmac_f32_e32 v243, v61, v61
	v_fmac_f32_e32 v244, v57, v57
	v_fmac_f32_e32 v245, v53, v53
	v_fmac_f32_e32 v221, v49, v49
	v_fmac_f32_e32 v222, v45, v45
	v_fmac_f32_e32 v223, v41, v41
	v_fmac_f32_e32 v224, v37, v37
	v_add_f32_e32 v242, v242, v243
	v_add_f32_e32 v244, v244, v245
	v_add_f32_e32 v251, v242, v244
	v_add_f32_e32 v221, v221, v222
	v_add_f32_e32 v223, v223, v224
	v_add_f32_e32 v252, v221, v223
	v_mul_f32_e32 v242, v30, v30
	v_mul_f32_e32 v243, v26, v26
	v_mul_f32_e32 v244, v22, v22
	v_mul_f32_e32 v245, v18, v18
	v_mul_f32_e32 v221, v14, v14
	v_mul_f32_e32 v222, v10, v10
	v_mul_f32_e32 v223, v6, v6
	v_mul_f32_e32 v224, v2, v2
	v_fmac_f32_e32 v242, v31, v31
	v_fmac_f32_e32 v243, v27, v27
	v_fmac_f32_e32 v244, v23, v23
	v_fmac_f32_e32 v245, v19, v19
	v_fmac_f32_e32 v221, v15, v15
	v_fmac_f32_e32 v222, v11, v11
	v_fmac_f32_e32 v223, v7, v7
	v_fmac_f32_e32 v224, v3, v3
	v_fmac_f32_e32 v242, v32, v32
	v_fmac_f32_e32 v243, v28, v28
	v_fmac_f32_e32 v244, v24, v24
	v_fmac_f32_e32 v245, v20, v20
	v_fmac_f32_e32 v221, v16, v16
	v_fmac_f32_e32 v222, v12, v12
	v_fmac_f32_e32 v223, v8, v8
	v_fmac_f32_e32 v224, v4, v4
	v_fmac_f32_e32 v242, v33, v33
	v_fmac_f32_e32 v243, v29, v29
	v_fmac_f32_e32 v244, v25, v25
	v_fmac_f32_e32 v245, v21, v21
	v_fmac_f32_e32 v221, v17, v17
	v_fmac_f32_e32 v222, v13, v13
	v_fmac_f32_e32 v223, v9, v9
	v_fmac_f32_e32 v224, v5, v5
	v_add_f32_e32 v242, v242, v243
	v_add_f32_e32 v244, v244, v245
	v_add_f32_e32 v253, v242, v244
	v_add_f32_e32 v221, v221, v222
	v_add_f32_e32 v223, v223, v224
	v_add_f32_e32 v254, v221, v223
	ds_bpermute_b32 v194, v212, v247
	ds_bpermute_b32 v195, v212, v248
	ds_bpermute_b32 v196, v212, v249
	ds_bpermute_b32 v197, v212, v250
	ds_bpermute_b32 v198, v212, v251
	ds_bpermute_b32 v199, v212, v252
	ds_bpermute_b32 v200, v212, v253
	ds_bpermute_b32 v201, v212, v254
	s_waitcnt lgkmcnt(0)
	v_add_f32_e32 v247, v247, v194
	v_add_f32_e32 v248, v248, v195
	v_add_f32_e32 v249, v249, v196
	v_add_f32_e32 v250, v250, v197
	v_add_f32_e32 v251, v251, v198
	v_add_f32_e32 v252, v252, v199
	v_add_f32_e32 v253, v253, v200
	v_add_f32_e32 v254, v254, v201
	ds_bpermute_b32 v194, v213, v247
	ds_bpermute_b32 v195, v213, v248
	ds_bpermute_b32 v196, v213, v249
	ds_bpermute_b32 v197, v213, v250
	ds_bpermute_b32 v198, v213, v251
	ds_bpermute_b32 v199, v213, v252
	ds_bpermute_b32 v200, v213, v253
	ds_bpermute_b32 v201, v213, v254
	s_waitcnt lgkmcnt(0)
	v_add_f32_e32 v247, v247, v194
	v_add_f32_e32 v248, v248, v195
	v_add_f32_e32 v249, v249, v196
	v_add_f32_e32 v250, v250, v197
	v_add_f32_e32 v251, v251, v198
	v_add_f32_e32 v252, v252, v199
	v_add_f32_e32 v253, v253, v200
	v_add_f32_e32 v254, v254, v201
	s_cmp_lt_i32 s10, 48
	s_movk_i32 s0, 0x1800
	s_cselect_b32 s0, s0, 0x3000
	s_cmp_gt_i32 s10, 31
	s_cselect_b32 s0, s0, 0
	s_lshl_b32 s0, s0, 2
	s_add_u32 s46, s92, s0
	s_addc_u32 s47, s93, 0
	s_add_u32 s46, s46, 0x40000
	s_addc_u32 s47, s47, 0
	s_add_u32 s48, s46, 0x2000
	s_addc_u32 s49, s47, 0
	s_add_u32 s38, s80, 0x2000
	s_addc_u32 s39, s81, 0
	s_add_u32 s44, s92, 0x20000
	s_addc_u32 s45, s93, 0
	global_load_dwordx4 v[226:229], v214, s[48:49]
	global_load_dwordx4 v[194:197], v214, s[38:39]
	global_load_dwordx4 v[230:233], v214, s[48:49] offset:16
	global_load_dwordx4 v[198:201], v214, s[38:39] offset:16
	global_load_dwordx4 v[234:237], v214, s[48:49] offset:512
	global_load_dwordx4 v[202:205], v214, s[38:39] offset:512
	global_load_dwordx4 v[238:241], v214, s[48:49] offset:528
	global_load_dwordx4 v[206:209], v214, s[38:39] offset:528
	v_cmp_eq_u32_e32 vcc, 0, v1
	s_nop 1
	s_and_saveexec_b64 s[12:13], vcc
	global_atomic_add_f32 v211, v247, s[44:45]
	global_atomic_add_f32 v211, v248, s[44:45] offset:64
	global_atomic_add_f32 v211, v249, s[44:45] offset:128
	global_atomic_add_f32 v211, v250, s[44:45] offset:192
	global_atomic_add_f32 v211, v251, s[44:45] offset:512
	global_atomic_add_f32 v211, v252, s[44:45] offset:576
	global_atomic_add_f32 v211, v253, s[44:45] offset:640
	global_atomic_add_f32 v211, v254, s[44:45] offset:704
	s_or_b64 exec, exec, s[12:13]
	s_waitcnt vmcnt(8)
	v_pk_add_f32 v[226:227], v[226:227], v[194:195]
	v_pk_add_f32 v[228:229], v[228:229], v[196:197]
	v_pk_add_f32 v[230:231], v[230:231], v[198:199]
	v_pk_add_f32 v[232:233], v[232:233], v[200:201]
	v_pk_add_f32 v[234:235], v[234:235], v[202:203]
	v_pk_add_f32 v[236:237], v[236:237], v[204:205]
	v_pk_add_f32 v[238:239], v[238:239], v[206:207]
	v_pk_add_f32 v[240:241], v[240:241], v[208:209]
	global_load_dwordx4 v[194:197], v214, s[52:53]
	global_load_dwordx4 v[198:201], v214, s[52:53] offset:16
	global_load_dwordx4 v[202:205], v214, s[52:53] offset:512
	global_load_dwordx4 v[206:209], v214, s[52:53] offset:528
	s_waitcnt vmcnt(0) lgkmcnt(0)
	s_barrier
	s_mov_b64 s[0:1], exec
	v_readlane_b32 s4, v246, 2
	v_readlane_b32 s5, v246, 3
	s_and_b64 s[4:5], s[0:1], s[4:5]
	s_mov_b64 exec, s[4:5]
	s_cbranch_execz .Lp7_s1_done
	s_lshl_b32 s4, s10, 8
	s_add_u32 s4, s92, s4
	s_addc_u32 s5, s93, 0
	s_add_u32 s4, s4, 0x4000
	s_addc_u32 s5, s5, 0
	v_mov_b32_e32 v219, 0
	v_mov_b32_e32 v220, 1
	global_atomic_add v219, v220, s[4:5]
	s_mov_b32 s8, 0x400000
.Lp7_s1_poll:
	global_load_dword v220, v219, s[4:5] sc1
	s_waitcnt vmcnt(0)
	v_cmp_lt_u32_e32 vcc, 3, v220
	s_cbranch_vccnz .Lp7_s1_done
	s_sleep 1
	s_sub_u32 s8, s8, 1
	s_cmp_lg_u32 s8, 0
	s_cbranch_scc1 .Lp7_s1_poll
.Lp7_s1_done:
	s_mov_b64 exec, s[0:1]
	s_barrier
	global_load_dword v247, v211, s[44:45] sc1
	global_load_dword v248, v211, s[44:45] offset:64 sc1
	global_load_dword v249, v211, s[44:45] offset:128 sc1
	global_load_dword v250, v211, s[44:45] offset:192 sc1
	global_load_dword v251, v211, s[44:45] offset:512 sc1
	global_load_dword v252, v211, s[44:45] offset:576 sc1
	global_load_dword v253, v211, s[44:45] offset:640 sc1
	global_load_dword v254, v211, s[44:45] offset:704 sc1
	v_pk_mul_f32 v[226:227], v[226:227], v[194:195]
	v_pk_mul_f32 v[228:229], v[228:229], v[196:197]
	v_pk_mul_f32 v[230:231], v[230:231], v[198:199]
	v_pk_mul_f32 v[232:233], v[232:233], v[200:201]
	v_pk_mul_f32 v[234:235], v[234:235], v[202:203]
	v_pk_mul_f32 v[236:237], v[236:237], v[204:205]
	v_pk_mul_f32 v[238:239], v[238:239], v[206:207]
	v_pk_mul_f32 v[240:241], v[240:241], v[208:209]
	s_add_u32 s36, s40, 0x80000
	s_addc_u32 s37, s41, 0
	global_load_dwordx4 v[194:197], v210, s[36:37]
	global_load_dwordx4 v[198:201], v210, s[36:37] offset:16
	global_load_dwordx4 v[202:205], v210, s[36:37] offset:512
	global_load_dwordx4 v[206:209], v210, s[36:37] offset:528
	v_mov_b32_e32 v218, 0x358637bd
	s_mov_b32 s9, 0x3a800000
	s_waitcnt vmcnt(4)
	v_fma_f32 v247, v247, s9, v218
	v_fma_f32 v248, v248, s9, v218
	v_fma_f32 v249, v249, s9, v218
	v_fma_f32 v250, v250, s9, v218
	v_fma_f32 v251, v251, s9, v218
	v_fma_f32 v252, v252, s9, v218
	v_fma_f32 v253, v253, s9, v218
	v_fma_f32 v254, v254, s9, v218
	v_rsq_f32_e32 v247, v247
	v_rsq_f32_e32 v248, v248
	v_rsq_f32_e32 v249, v249
	v_rsq_f32_e32 v250, v250
	v_rsq_f32_e32 v251, v251
	v_rsq_f32_e32 v252, v252
	v_rsq_f32_e32 v253, v253
	v_rsq_f32_e32 v254, v254
	s_nop 0
	v_mov_b32_e32 v216, v247
	v_pk_mul_f32 v[126:127], v[126:127], v[216:217] op_sel_hi:[1,0]
	v_pk_mul_f32 v[128:129], v[128:129], v[216:217] op_sel_hi:[1,0]
	v_pk_mul_f32 v[122:123], v[122:123], v[216:217] op_sel_hi:[1,0]
	v_pk_mul_f32 v[124:125], v[124:125], v[216:217] op_sel_hi:[1,0]
	v_pk_mul_f32 v[118:119], v[118:119], v[216:217] op_sel_hi:[1,0]
	v_pk_mul_f32 v[120:121], v[120:121], v[216:217] op_sel_hi:[1,0]
	v_pk_mul_f32 v[110:111], v[110:111], v[216:217] op_sel_hi:[1,0]
	v_pk_mul_f32 v[112:113], v[112:113], v[216:217] op_sel_hi:[1,0]
	v_pk_fma_f32 v[126:127], v[226:227], v[126:127], v[130:131]
	v_pk_fma_f32 v[128:129], v[228:229], v[128:129], v[132:133]
	v_pk_fma_f32 v[122:123], v[230:231], v[122:123], v[134:135]
	v_pk_fma_f32 v[124:125], v[232:233], v[124:125], v[136:137]
	v_pk_fma_f32 v[118:119], v[234:235], v[118:119], v[138:139]
	v_pk_fma_f32 v[120:121], v[236:237], v[120:121], v[140:141]
	v_pk_fma_f32 v[110:111], v[238:239], v[110:111], v[142:143]
	v_pk_fma_f32 v[112:113], v[240:241], v[112:113], v[144:145]
	s_add_u32 s34, s90, 0x0
	s_addc_u32 s35, s91, 0
	global_store_dwordx4 v210, v[126:129], s[34:35]
	global_store_dwordx4 v210, v[122:125], s[34:35] offset:16
	global_store_dwordx4 v210, v[118:121], s[34:35] offset:512
	global_store_dwordx4 v210, v[110:113], s[34:35] offset:528
	s_add_u32 s36, s40, 0x90000
	s_addc_u32 s37, s41, 0
	global_load_dwordx4 v[130:133], v210, s[36:37]
	global_load_dwordx4 v[134:137], v210, s[36:37] offset:16
	global_load_dwordx4 v[138:141], v210, s[36:37] offset:512
	global_load_dwordx4 v[142:145], v210, s[36:37] offset:528
	v_mov_b32_e32 v216, v248
	v_pk_mul_f32 v[114:115], v[114:115], v[216:217] op_sel_hi:[1,0]
	v_pk_mul_f32 v[116:117], v[116:117], v[216:217] op_sel_hi:[1,0]
	v_pk_mul_f32 v[106:107], v[106:107], v[216:217] op_sel_hi:[1,0]
	v_pk_mul_f32 v[108:109], v[108:109], v[216:217] op_sel_hi:[1,0]
	v_pk_mul_f32 v[102:103], v[102:103], v[216:217] op_sel_hi:[1,0]
	v_pk_mul_f32 v[104:105], v[104:105], v[216:217] op_sel_hi:[1,0]
	v_pk_mul_f32 v[98:99], v[98:99], v[216:217] op_sel_hi:[1,0]
	v_pk_mul_f32 v[100:101], v[100:101], v[216:217] op_sel_hi:[1,0]
	v_pk_fma_f32 v[114:115], v[226:227], v[114:115], v[146:147]
	v_pk_fma_f32 v[116:117], v[228:229], v[116:117], v[148:149]
	v_pk_fma_f32 v[106:107], v[230:231], v[106:107], v[150:151]
	v_pk_fma_f32 v[108:109], v[232:233], v[108:109], v[152:153]
	v_pk_fma_f32 v[102:103], v[234:235], v[102:103], v[154:155]
	v_pk_fma_f32 v[104:105], v[236:237], v[104:105], v[156:157]
	v_pk_fma_f32 v[98:99], v[238:239], v[98:99], v[158:159]
	v_pk_fma_f32 v[100:101], v[240:241], v[100:101], v[160:161]
	s_add_u32 s34, s90, 0x10000
	s_addc_u32 s35, s91, 0
	global_store_dwordx4 v210, v[114:117], s[34:35]
	global_store_dwordx4 v210, v[106:109], s[34:35] offset:16
	global_store_dwordx4 v210, v[102:105], s[34:35] offset:512
	global_store_dwordx4 v210, v[98:101], s[34:35] offset:528
	s_add_u32 s36, s40, 0xa0000
	s_addc_u32 s37, s41, 0
	global_load_dwordx4 v[146:149], v210, s[36:37]
	global_load_dwordx4 v[150:153], v210, s[36:37] offset:16
	global_load_dwordx4 v[154:157], v210, s[36:37] offset:512
	global_load_dwordx4 v[158:161], v210, s[36:37] offset:528
	v_mov_b32_e32 v216, v249
	v_pk_mul_f32 v[94:95], v[94:95], v[216:217] op_sel_hi:[1,0]
	v_pk_mul_f32 v[96:97], v[96:97], v[216:217] op_sel_hi:[1,0]
	v_pk_mul_f32 v[90:91], v[90:91], v[216:217] op_sel_hi:[1,0]
	v_pk_mul_f32 v[92:93], v[92:93], v[216:217] op_sel_hi:[1,0]
	v_pk_mul_f32 v[86:87], v[86:87], v[216:217] op_sel_hi:[1,0]
	v_pk_mul_f32 v[88:89], v[88:89], v[216:217] op_sel_hi:[1,0]
	v_pk_mul_f32 v[82:83], v[82:83], v[216:217] op_sel_hi:[1,0]
	v_pk_mul_f32 v[84:85], v[84:85], v[216:217] op_sel_hi:[1,0]
	v_pk_fma_f32 v[94:95], v[226:227], v[94:95], v[162:163]
	v_pk_fma_f32 v[96:97], v[228:229], v[96:97], v[164:165]
	v_pk_fma_f32 v[90:91], v[230:231], v[90:91], v[166:167]
	v_pk_fma_f32 v[92:93], v[232:233], v[92:93], v[168:169]
	v_pk_fma_f32 v[86:87], v[234:235], v[86:87], v[170:171]
	v_pk_fma_f32 v[88:89], v[236:237], v[88:89], v[172:173]
	v_pk_fma_f32 v[82:83], v[238:239], v[82:83], v[174:175]
	v_pk_fma_f32 v[84:85], v[240:241], v[84:85], v[176:177]
	s_add_u32 s34, s90, 0x20000
	s_addc_u32 s35, s91, 0
	global_store_dwordx4 v210, v[94:97], s[34:35]
	global_store_dwordx4 v210, v[90:93], s[34:35] offset:16
	global_store_dwordx4 v210, v[86:89], s[34:35] offset:512
	global_store_dwordx4 v210, v[82:85], s[34:35] offset:528
	s_add_u32 s36, s40, 0xb0000
	s_addc_u32 s37, s41, 0
	global_load_dwordx4 v[162:165], v210, s[36:37]
	global_load_dwordx4 v[166:169], v210, s[36:37] offset:16
	global_load_dwordx4 v[170:173], v210, s[36:37] offset:512
	global_load_dwordx4 v[174:177], v210, s[36:37] offset:528
	v_mov_b32_e32 v216, v250
	v_pk_mul_f32 v[78:79], v[78:79], v[216:217] op_sel_hi:[1,0]
	v_pk_mul_f32 v[80:81], v[80:81], v[216:217] op_sel_hi:[1,0]
	v_pk_mul_f32 v[74:75], v[74:75], v[216:217] op_sel_hi:[1,0]
	v_pk_mul_f32 v[76:77], v[76:77], v[216:217] op_sel_hi:[1,0]
	v_pk_mul_f32 v[70:71], v[70:71], v[216:217] op_sel_hi:[1,0]
	v_pk_mul_f32 v[72:73], v[72:73], v[216:217] op_sel_hi:[1,0]
	v_pk_mul_f32 v[66:67], v[66:67], v[216:217] op_sel_hi:[1,0]
	v_pk_mul_f32 v[68:69], v[68:69], v[216:217] op_sel_hi:[1,0]
	v_pk_fma_f32 v[78:79], v[226:227], v[78:79], v[178:179]
	v_pk_fma_f32 v[80:81], v[228:229], v[80:81], v[180:181]
	v_pk_fma_f32 v[74:75], v[230:231], v[74:75], v[182:183]
	v_pk_fma_f32 v[76:77], v[232:233], v[76:77], v[184:185]
	v_pk_fma_f32 v[70:71], v[234:235], v[70:71], v[186:187]
	v_pk_fma_f32 v[72:73], v[236:237], v[72:73], v[188:189]
	v_pk_fma_f32 v[66:67], v[238:239], v[66:67], v[190:191]
	v_pk_fma_f32 v[68:69], v[240:241], v[68:69], v[192:193]
	s_add_u32 s34, s90, 0x30000
	s_addc_u32 s35, s91, 0
	global_store_dwordx4 v210, v[78:81], s[34:35]
	global_store_dwordx4 v210, v[74:77], s[34:35] offset:16
	global_store_dwordx4 v210, v[70:73], s[34:35] offset:512
	global_store_dwordx4 v210, v[66:69], s[34:35] offset:528
	s_waitcnt vmcnt(28)
	v_mov_b32_e32 v216, v251
	v_pk_mul_f32 v[62:63], v[62:63], v[216:217] op_sel_hi:[1,0]
	v_pk_mul_f32 v[64:65], v[64:65], v[216:217] op_sel_hi:[1,0]
	v_pk_mul_f32 v[58:59], v[58:59], v[216:217] op_sel_hi:[1,0]
	v_pk_mul_f32 v[60:61], v[60:61], v[216:217] op_sel_hi:[1,0]
	v_pk_mul_f32 v[54:55], v[54:55], v[216:217] op_sel_hi:[1,0]
	v_pk_mul_f32 v[56:57], v[56:57], v[216:217] op_sel_hi:[1,0]
	v_pk_mul_f32 v[50:51], v[50:51], v[216:217] op_sel_hi:[1,0]
	v_pk_mul_f32 v[52:53], v[52:53], v[216:217] op_sel_hi:[1,0]
	v_pk_fma_f32 v[62:63], v[226:227], v[62:63], v[194:195]
	v_pk_fma_f32 v[64:65], v[228:229], v[64:65], v[196:197]
	v_pk_fma_f32 v[58:59], v[230:231], v[58:59], v[198:199]
	v_pk_fma_f32 v[60:61], v[232:233], v[60:61], v[200:201]
	v_pk_fma_f32 v[54:55], v[234:235], v[54:55], v[202:203]
	v_pk_fma_f32 v[56:57], v[236:237], v[56:57], v[204:205]
	v_pk_fma_f32 v[50:51], v[238:239], v[50:51], v[206:207]
	v_pk_fma_f32 v[52:53], v[240:241], v[52:53], v[208:209]
	s_add_u32 s34, s90, 0x80000
	s_addc_u32 s35, s91, 0
	global_store_dwordx4 v210, v[62:65], s[34:35]
	global_store_dwordx4 v210, v[58:61], s[34:35] offset:16
	global_store_dwordx4 v210, v[54:57], s[34:35] offset:512
	global_store_dwordx4 v210, v[50:53], s[34:35] offset:528
	s_waitcnt vmcnt(24)
	v_mov_b32_e32 v216, v252
	v_pk_mul_f32 v[46:47], v[46:47], v[216:217] op_sel_hi:[1,0]
	v_pk_mul_f32 v[48:49], v[48:49], v[216:217] op_sel_hi:[1,0]
	v_pk_mul_f32 v[42:43], v[42:43], v[216:217] op_sel_hi:[1,0]
	v_pk_mul_f32 v[44:45], v[44:45], v[216:217] op_sel_hi:[1,0]
	v_pk_mul_f32 v[38:39], v[38:39], v[216:217] op_sel_hi:[1,0]
	v_pk_mul_f32 v[40:41], v[40:41], v[216:217] op_sel_hi:[1,0]
	v_pk_mul_f32 v[34:35], v[34:35], v[216:217] op_sel_hi:[1,0]
	v_pk_mul_f32 v[36:37], v[36:37], v[216:217] op_sel_hi:[1,0]
	v_pk_fma_f32 v[46:47], v[226:227], v[46:47], v[130:131]
	v_pk_fma_f32 v[48:49], v[228:229], v[48:49], v[132:133]
	v_pk_fma_f32 v[42:43], v[230:231], v[42:43], v[134:135]
	v_pk_fma_f32 v[44:45], v[232:233], v[44:45], v[136:137]
	v_pk_fma_f32 v[38:39], v[234:235], v[38:39], v[138:139]
	v_pk_fma_f32 v[40:41], v[236:237], v[40:41], v[140:141]
	v_pk_fma_f32 v[34:35], v[238:239], v[34:35], v[142:143]
	v_pk_fma_f32 v[36:37], v[240:241], v[36:37], v[144:145]
	s_add_u32 s34, s90, 0x90000
	s_addc_u32 s35, s91, 0
	global_store_dwordx4 v210, v[46:49], s[34:35]
	global_store_dwordx4 v210, v[42:45], s[34:35] offset:16
	global_store_dwordx4 v210, v[38:41], s[34:35] offset:512
	global_store_dwordx4 v210, v[34:37], s[34:35] offset:528
	s_waitcnt vmcnt(20)
	v_mov_b32_e32 v216, v253
	v_pk_mul_f32 v[30:31], v[30:31], v[216:217] op_sel_hi:[1,0]
	v_pk_mul_f32 v[32:33], v[32:33], v[216:217] op_sel_hi:[1,0]
	v_pk_mul_f32 v[26:27], v[26:27], v[216:217] op_sel_hi:[1,0]
	v_pk_mul_f32 v[28:29], v[28:29], v[216:217] op_sel_hi:[1,0]
	v_pk_mul_f32 v[22:23], v[22:23], v[216:217] op_sel_hi:[1,0]
	v_pk_mul_f32 v[24:25], v[24:25], v[216:217] op_sel_hi:[1,0]
	v_pk_mul_f32 v[18:19], v[18:19], v[216:217] op_sel_hi:[1,0]
	v_pk_mul_f32 v[20:21], v[20:21], v[216:217] op_sel_hi:[1,0]
	v_pk_fma_f32 v[30:31], v[226:227], v[30:31], v[146:147]
	v_pk_fma_f32 v[32:33], v[228:229], v[32:33], v[148:149]
	v_pk_fma_f32 v[26:27], v[230:231], v[26:27], v[150:151]
	v_pk_fma_f32 v[28:29], v[232:233], v[28:29], v[152:153]
	v_pk_fma_f32 v[22:23], v[234:235], v[22:23], v[154:155]
	v_pk_fma_f32 v[24:25], v[236:237], v[24:25], v[156:157]
	v_pk_fma_f32 v[18:19], v[238:239], v[18:19], v[158:159]
	v_pk_fma_f32 v[20:21], v[240:241], v[20:21], v[160:161]
	s_add_u32 s34, s90, 0xa0000
	s_addc_u32 s35, s91, 0
	global_store_dwordx4 v210, v[30:33], s[34:35]
	global_store_dwordx4 v210, v[26:29], s[34:35] offset:16
	global_store_dwordx4 v210, v[22:25], s[34:35] offset:512
	global_store_dwordx4 v210, v[18:21], s[34:35] offset:528
	s_waitcnt vmcnt(16)
	v_mov_b32_e32 v216, v254
	v_pk_mul_f32 v[14:15], v[14:15], v[216:217] op_sel_hi:[1,0]
	v_pk_mul_f32 v[16:17], v[16:17], v[216:217] op_sel_hi:[1,0]
	v_pk_mul_f32 v[10:11], v[10:11], v[216:217] op_sel_hi:[1,0]
	v_pk_mul_f32 v[12:13], v[12:13], v[216:217] op_sel_hi:[1,0]
	v_pk_mul_f32 v[6:7], v[6:7], v[216:217] op_sel_hi:[1,0]
	v_pk_mul_f32 v[8:9], v[8:9], v[216:217] op_sel_hi:[1,0]
	v_pk_mul_f32 v[2:3], v[2:3], v[216:217] op_sel_hi:[1,0]
	v_pk_mul_f32 v[4:5], v[4:5], v[216:217] op_sel_hi:[1,0]
	v_pk_fma_f32 v[14:15], v[226:227], v[14:15], v[162:163]
	v_pk_fma_f32 v[16:17], v[228:229], v[16:17], v[164:165]
	v_pk_fma_f32 v[10:11], v[230:231], v[10:11], v[166:167]
	v_pk_fma_f32 v[12:13], v[232:233], v[12:13], v[168:169]
	v_pk_fma_f32 v[6:7], v[234:235], v[6:7], v[170:171]
	v_pk_fma_f32 v[8:9], v[236:237], v[8:9], v[172:173]
	v_pk_fma_f32 v[2:3], v[238:239], v[2:3], v[174:175]
	v_pk_fma_f32 v[4:5], v[240:241], v[4:5], v[176:177]
	s_add_u32 s34, s90, 0xb0000
	s_addc_u32 s35, s91, 0
	global_store_dwordx4 v210, v[14:17], s[34:35]
	global_store_dwordx4 v210, v[10:13], s[34:35] offset:16
	global_store_dwordx4 v210, v[6:9], s[34:35] offset:512
	global_store_dwordx4 v210, v[2:5], s[34:35] offset:528
	v_mul_f32_e32 v242, v126, v126
	v_mul_f32_e32 v243, v122, v122
	v_mul_f32_e32 v244, v118, v118
	v_mul_f32_e32 v245, v110, v110
	v_mul_f32_e32 v221, v114, v114
	v_mul_f32_e32 v222, v106, v106
	v_mul_f32_e32 v223, v102, v102
	v_mul_f32_e32 v224, v98, v98
	v_fmac_f32_e32 v242, v127, v127
	v_fmac_f32_e32 v243, v123, v123
	v_fmac_f32_e32 v244, v119, v119
	v_fmac_f32_e32 v245, v111, v111
	v_fmac_f32_e32 v221, v115, v115
	v_fmac_f32_e32 v222, v107, v107
	v_fmac_f32_e32 v223, v103, v103
	v_fmac_f32_e32 v224, v99, v99
	v_fmac_f32_e32 v242, v128, v128
	v_fmac_f32_e32 v243, v124, v124
	v_fmac_f32_e32 v244, v120, v120
	v_fmac_f32_e32 v245, v112, v112
	v_fmac_f32_e32 v221, v116, v116
	v_fmac_f32_e32 v222, v108, v108
	v_fmac_f32_e32 v223, v104, v104
	v_fmac_f32_e32 v224, v100, v100
	v_fmac_f32_e32 v242, v129, v129
	v_fmac_f32_e32 v243, v125, v125
	v_fmac_f32_e32 v244, v121, v121
	v_fmac_f32_e32 v245, v113, v113
	v_fmac_f32_e32 v221, v117, v117
	v_fmac_f32_e32 v222, v109, v109
	v_fmac_f32_e32 v223, v105, v105
	v_fmac_f32_e32 v224, v101, v101
	v_add_f32_e32 v242, v242, v243
	v_add_f32_e32 v244, v244, v245
	v_add_f32_e32 v247, v242, v244
	v_add_f32_e32 v221, v221, v222
	v_add_f32_e32 v223, v223, v224
	v_add_f32_e32 v248, v221, v223
	v_mul_f32_e32 v242, v94, v94
	v_mul_f32_e32 v243, v90, v90
	v_mul_f32_e32 v244, v86, v86
	v_mul_f32_e32 v245, v82, v82
	v_mul_f32_e32 v221, v78, v78
	v_mul_f32_e32 v222, v74, v74
	v_mul_f32_e32 v223, v70, v70
	v_mul_f32_e32 v224, v66, v66
	v_fmac_f32_e32 v242, v95, v95
	v_fmac_f32_e32 v243, v91, v91
	v_fmac_f32_e32 v244, v87, v87
	v_fmac_f32_e32 v245, v83, v83
	v_fmac_f32_e32 v221, v79, v79
	v_fmac_f32_e32 v222, v75, v75
	v_fmac_f32_e32 v223, v71, v71
	v_fmac_f32_e32 v224, v67, v67
	v_fmac_f32_e32 v242, v96, v96
	v_fmac_f32_e32 v243, v92, v92
	v_fmac_f32_e32 v244, v88, v88
	v_fmac_f32_e32 v245, v84, v84
	v_fmac_f32_e32 v221, v80, v80
	v_fmac_f32_e32 v222, v76, v76
	v_fmac_f32_e32 v223, v72, v72
	v_fmac_f32_e32 v224, v68, v68
	v_fmac_f32_e32 v242, v97, v97
	v_fmac_f32_e32 v243, v93, v93
	v_fmac_f32_e32 v244, v89, v89
	v_fmac_f32_e32 v245, v85, v85
	v_fmac_f32_e32 v221, v81, v81
	v_fmac_f32_e32 v222, v77, v77
	v_fmac_f32_e32 v223, v73, v73
	v_fmac_f32_e32 v224, v69, v69
	v_add_f32_e32 v242, v242, v243
	v_add_f32_e32 v244, v244, v245
	v_add_f32_e32 v249, v242, v244
	v_add_f32_e32 v221, v221, v222
	v_add_f32_e32 v223, v223, v224
	v_add_f32_e32 v250, v221, v223
	v_mul_f32_e32 v242, v62, v62
	v_mul_f32_e32 v243, v58, v58
	v_mul_f32_e32 v244, v54, v54
	v_mul_f32_e32 v245, v50, v50
	v_mul_f32_e32 v221, v46, v46
	v_mul_f32_e32 v222, v42, v42
	v_mul_f32_e32 v223, v38, v38
	v_mul_f32_e32 v224, v34, v34
	v_fmac_f32_e32 v242, v63, v63
	v_fmac_f32_e32 v243, v59, v59
	v_fmac_f32_e32 v244, v55, v55
	v_fmac_f32_e32 v245, v51, v51
	v_fmac_f32_e32 v221, v47, v47
	v_fmac_f32_e32 v222, v43, v43
	v_fmac_f32_e32 v223, v39, v39
	v_fmac_f32_e32 v224, v35, v35
	v_fmac_f32_e32 v242, v64, v64
	v_fmac_f32_e32 v243, v60, v60
	v_fmac_f32_e32 v244, v56, v56
	v_fmac_f32_e32 v245, v52, v52
	v_fmac_f32_e32 v221, v48, v48
	v_fmac_f32_e32 v222, v44, v44
	v_fmac_f32_e32 v223, v40, v40
	v_fmac_f32_e32 v224, v36, v36
	v_fmac_f32_e32 v242, v65, v65
	v_fmac_f32_e32 v243, v61, v61
	v_fmac_f32_e32 v244, v57, v57
	v_fmac_f32_e32 v245, v53, v53
	v_fmac_f32_e32 v221, v49, v49
	v_fmac_f32_e32 v222, v45, v45
	v_fmac_f32_e32 v223, v41, v41
	v_fmac_f32_e32 v224, v37, v37
	v_add_f32_e32 v242, v242, v243
	v_add_f32_e32 v244, v244, v245
	v_add_f32_e32 v251, v242, v244
	v_add_f32_e32 v221, v221, v222
	v_add_f32_e32 v223, v223, v224
	v_add_f32_e32 v252, v221, v223
	v_mul_f32_e32 v242, v30, v30
	v_mul_f32_e32 v243, v26, v26
	v_mul_f32_e32 v244, v22, v22
	v_mul_f32_e32 v245, v18, v18
	v_mul_f32_e32 v221, v14, v14
	v_mul_f32_e32 v222, v10, v10
	v_mul_f32_e32 v223, v6, v6
	v_mul_f32_e32 v224, v2, v2
	v_fmac_f32_e32 v242, v31, v31
	v_fmac_f32_e32 v243, v27, v27
	v_fmac_f32_e32 v244, v23, v23
	v_fmac_f32_e32 v245, v19, v19
	v_fmac_f32_e32 v221, v15, v15
	v_fmac_f32_e32 v222, v11, v11
	v_fmac_f32_e32 v223, v7, v7
	v_fmac_f32_e32 v224, v3, v3
	v_fmac_f32_e32 v242, v32, v32
	v_fmac_f32_e32 v243, v28, v28
	v_fmac_f32_e32 v244, v24, v24
	v_fmac_f32_e32 v245, v20, v20
	v_fmac_f32_e32 v221, v16, v16
	v_fmac_f32_e32 v222, v12, v12
	v_fmac_f32_e32 v223, v8, v8
	v_fmac_f32_e32 v224, v4, v4
	v_fmac_f32_e32 v242, v33, v33
	v_fmac_f32_e32 v243, v29, v29
	v_fmac_f32_e32 v244, v25, v25
	v_fmac_f32_e32 v245, v21, v21
	v_fmac_f32_e32 v221, v17, v17
	v_fmac_f32_e32 v222, v13, v13
	v_fmac_f32_e32 v223, v9, v9
	v_fmac_f32_e32 v224, v5, v5
	v_add_f32_e32 v242, v242, v243
	v_add_f32_e32 v244, v244, v245
	v_add_f32_e32 v253, v242, v244
	v_add_f32_e32 v221, v221, v222
	v_add_f32_e32 v223, v223, v224
	v_add_f32_e32 v254, v221, v223
	ds_bpermute_b32 v194, v212, v247
	ds_bpermute_b32 v195, v212, v248
	ds_bpermute_b32 v196, v212, v249
	ds_bpermute_b32 v197, v212, v250
	ds_bpermute_b32 v198, v212, v251
	ds_bpermute_b32 v199, v212, v252
	ds_bpermute_b32 v200, v212, v253
	ds_bpermute_b32 v201, v212, v254
	s_waitcnt lgkmcnt(0)
	v_add_f32_e32 v247, v247, v194
	v_add_f32_e32 v248, v248, v195
	v_add_f32_e32 v249, v249, v196
	v_add_f32_e32 v250, v250, v197
	v_add_f32_e32 v251, v251, v198
	v_add_f32_e32 v252, v252, v199
	v_add_f32_e32 v253, v253, v200
	v_add_f32_e32 v254, v254, v201
	ds_bpermute_b32 v194, v213, v247
	ds_bpermute_b32 v195, v213, v248
	ds_bpermute_b32 v196, v213, v249
	ds_bpermute_b32 v197, v213, v250
	ds_bpermute_b32 v198, v213, v251
	ds_bpermute_b32 v199, v213, v252
	ds_bpermute_b32 v200, v213, v253
	ds_bpermute_b32 v201, v213, v254
	s_waitcnt lgkmcnt(0)
	v_add_f32_e32 v247, v247, v194
	v_add_f32_e32 v248, v248, v195
	v_add_f32_e32 v249, v249, v196
	v_add_f32_e32 v250, v250, v197
	v_add_f32_e32 v251, v251, v198
	v_add_f32_e32 v252, v252, v199
	v_add_f32_e32 v253, v253, v200
	v_add_f32_e32 v254, v254, v201
	s_add_u32 s44, s92, 0x60000
	s_addc_u32 s45, s93, 0
	v_cmp_eq_u32_e32 vcc, 0, v1
	s_nop 1
	s_and_saveexec_b64 s[12:13], vcc
	global_atomic_add_f32 v211, v247, s[44:45]
	global_atomic_add_f32 v211, v248, s[44:45] offset:64
	global_atomic_add_f32 v211, v249, s[44:45] offset:128
	global_atomic_add_f32 v211, v250, s[44:45] offset:192
	global_atomic_add_f32 v211, v251, s[44:45] offset:512
	global_atomic_add_f32 v211, v252, s[44:45] offset:576
	global_atomic_add_f32 v211, v253, s[44:45] offset:640
	global_atomic_add_f32 v211, v254, s[44:45] offset:704
	s_or_b64 exec, exec, s[12:13]
	s_add_u32 s48, s46, 0x3000
	s_addc_u32 s49, s47, 0
	s_add_u32 s38, s80, 0x3000
	s_addc_u32 s39, s81, 0
	s_add_u32 s18, s46, 0x4000
	s_addc_u32 s19, s47, 0
	s_add_u32 s20, s80, 0x4000
	s_addc_u32 s21, s81, 0
	global_load_dwordx4 v[130:133], v214, s[54:55]
	global_load_dwordx4 v[146:149], v214, s[48:49]
	global_load_dwordx4 v[162:165], v214, s[38:39]
	global_load_dwordx4 v[178:181], v214, s[18:19]
	global_load_dwordx4 v[194:197], v214, s[20:21]
	global_load_dwordx4 v[134:137], v214, s[54:55] offset:16
	global_load_dwordx4 v[150:153], v214, s[48:49] offset:16
	global_load_dwordx4 v[166:169], v214, s[38:39] offset:16
	global_load_dwordx4 v[182:185], v214, s[18:19] offset:16
	global_load_dwordx4 v[198:201], v214, s[20:21] offset:16
	global_load_dwordx4 v[138:141], v214, s[54:55] offset:512
	global_load_dwordx4 v[154:157], v214, s[48:49] offset:512
	global_load_dwordx4 v[170:173], v214, s[38:39] offset:512
	global_load_dwordx4 v[186:189], v214, s[18:19] offset:512
	global_load_dwordx4 v[202:205], v214, s[20:21] offset:512
	global_load_dwordx4 v[142:145], v214, s[54:55] offset:528
	global_load_dwordx4 v[158:161], v214, s[48:49] offset:528
	global_load_dwordx4 v[174:177], v214, s[38:39] offset:528
	global_load_dwordx4 v[190:193], v214, s[18:19] offset:528
	global_load_dwordx4 v[206:209], v214, s[20:21] offset:528
	s_waitcnt vmcnt(0) lgkmcnt(0)
	s_barrier
	s_mov_b64 s[0:1], exec
	v_readlane_b32 s4, v246, 2
	v_readlane_b32 s5, v246, 3
	s_and_b64 s[4:5], s[0:1], s[4:5]
	s_mov_b64 exec, s[4:5]
	s_cbranch_execz .Lp7_s2_done
	s_lshl_b32 s4, s10, 8
	s_add_u32 s4, s92, s4
	s_addc_u32 s5, s93, 0
	s_add_u32 s4, s4, 0x8000
	s_addc_u32 s5, s5, 0
	v_mov_b32_e32 v219, 0
	v_mov_b32_e32 v220, 1
	global_atomic_add v219, v220, s[4:5]
	s_mov_b32 s8, 0x400000

.Lp7_s2_done:
	s_mov_b64 exec, s[0:1]
	s_barrier
	global_load_dword v247, v211, s[44:45] sc1
	global_load_dword v248, v211, s[44:45] offset:64 sc1
	global_load_dword v249, v211, s[44:45] offset:128 sc1
	global_load_dword v250, v211, s[44:45] offset:192 sc1
	global_load_dword v251, v211, s[44:45] offset:512 sc1
	global_load_dword v252, v211, s[44:45] offset:576 sc1
	global_load_dword v253, v211, s[44:45] offset:640 sc1
	global_load_dword v254, v211, s[44:45] offset:704 sc1
	v_pk_add_f32 v[146:147], v[146:147], v[162:163]
	v_pk_add_f32 v[178:179], v[178:179], v[194:195]
	v_pk_add_f32 v[148:149], v[148:149], v[164:165]
	v_pk_add_f32 v[180:181], v[180:181], v[196:197]
	v_pk_add_f32 v[150:151], v[150:151], v[166:167]
	v_pk_add_f32 v[182:183], v[182:183], v[198:199]
	v_pk_add_f32 v[152:153], v[152:153], v[168:169]
	v_pk_add_f32 v[184:185], v[184:185], v[200:201]
	v_pk_add_f32 v[154:155], v[154:155], v[170:171]
	v_pk_add_f32 v[186:187], v[186:187], v[202:203]
	v_pk_add_f32 v[156:157], v[156:157], v[172:173]
	v_pk_add_f32 v[188:189], v[188:189], v[204:205]
	v_pk_add_f32 v[158:159], v[158:159], v[174:175]
	v_pk_add_f32 v[190:191], v[190:191], v[206:207]
	v_pk_add_f32 v[160:161], v[160:161], v[176:177]
	v_pk_add_f32 v[192:193], v[192:193], v[208:209]
	v_pk_add_f32 v[178:179], v[178:179], 1.0 op_sel_hi:[1,0]
	v_pk_add_f32 v[180:181], v[180:181], 1.0 op_sel_hi:[1,0]
	v_pk_add_f32 v[182:183], v[182:183], 1.0 op_sel_hi:[1,0]
	v_pk_add_f32 v[184:185], v[184:185], 1.0 op_sel_hi:[1,0]
	v_pk_add_f32 v[186:187], v[186:187], 1.0 op_sel_hi:[1,0]
	v_pk_add_f32 v[188:189], v[188:189], 1.0 op_sel_hi:[1,0]
	v_pk_add_f32 v[190:191], v[190:191], 1.0 op_sel_hi:[1,0]
	v_pk_add_f32 v[192:193], v[192:193], 1.0 op_sel_hi:[1,0]
	v_pk_mul_f32 v[178:179], v[130:131], v[178:179]
	v_pk_mul_f32 v[180:181], v[132:133], v[180:181]
	v_pk_mul_f32 v[182:183], v[134:135], v[182:183]
	v_pk_mul_f32 v[184:185], v[136:137], v[184:185]
	v_pk_mul_f32 v[186:187], v[138:139], v[186:187]
	v_pk_mul_f32 v[188:189], v[140:141], v[188:189]
	v_pk_mul_f32 v[190:191], v[142:143], v[190:191]
	v_pk_mul_f32 v[192:193], v[144:145], v[192:193]
	s_waitcnt vmcnt(0)
	v_fma_f32 v247, v247, s9, v218
	v_fma_f32 v248, v248, s9, v218
	v_fma_f32 v249, v249, s9, v218
	v_fma_f32 v250, v250, s9, v218
	v_fma_f32 v251, v251, s9, v218
	v_fma_f32 v252, v252, s9, v218
	v_fma_f32 v253, v253, s9, v218
	v_fma_f32 v254, v254, s9, v218
	v_rsq_f32_e32 v247, v247
	v_rsq_f32_e32 v248, v248
	v_rsq_f32_e32 v249, v249
	v_rsq_f32_e32 v250, v250
	v_rsq_f32_e32 v251, v251
	v_rsq_f32_e32 v252, v252
	v_rsq_f32_e32 v253, v253
	v_rsq_f32_e32 v254, v254
	s_nop 0
	s_add_u32 s22, s92, 0x2800000
	s_addc_u32 s23, s93, 0
	v_mov_b32_e32 v216, v247
	v_pk_mul_f32 v[126:127], v[126:127], v[216:217] op_sel_hi:[1,0]
	v_pk_mul_f32 v[128:129], v[128:129], v[216:217] op_sel_hi:[1,0]
	v_pk_mul_f32 v[122:123], v[122:123], v[216:217] op_sel_hi:[1,0]
	v_pk_mul_f32 v[124:125], v[124:125], v[216:217] op_sel_hi:[1,0]
	v_pk_mul_f32 v[118:119], v[118:119], v[216:217] op_sel_hi:[1,0]
	v_pk_mul_f32 v[120:121], v[120:121], v[216:217] op_sel_hi:[1,0]
	v_pk_mul_f32 v[110:111], v[110:111], v[216:217] op_sel_hi:[1,0]
	v_pk_mul_f32 v[112:113], v[112:113], v[216:217] op_sel_hi:[1,0]
	v_pk_fma_f32 v[126:127], v[126:127], v[178:179], v[146:147]
	v_pk_fma_f32 v[128:129], v[128:129], v[180:181], v[148:149]
	v_pk_fma_f32 v[122:123], v[122:123], v[182:183], v[150:151]
	v_pk_fma_f32 v[124:125], v[124:125], v[184:185], v[152:153]
	v_pk_fma_f32 v[118:119], v[118:119], v[186:187], v[154:155]
	v_pk_fma_f32 v[120:121], v[120:121], v[188:189], v[156:157]
	v_pk_fma_f32 v[110:111], v[110:111], v[190:191], v[158:159]
	v_pk_fma_f32 v[112:113], v[112:113], v[192:193], v[160:161]
	s_add_u32 s34, s22, 0x0
	s_addc_u32 s35, s23, 0
	v_cvt_pk_bf16_f32 v162, v126, v127
	v_cvt_pk_bf16_f32 v163, v128, v129
	v_cvt_pk_bf16_f32 v164, v122, v123
	v_cvt_pk_bf16_f32 v165, v124, v125
	global_store_dwordx4 v215, v[162:165], s[34:35]
	v_cvt_pk_bf16_f32 v166, v118, v119
	v_cvt_pk_bf16_f32 v167, v120, v121
	v_cvt_pk_bf16_f32 v168, v110, v111
	v_cvt_pk_bf16_f32 v169, v112, v113
	global_store_dwordx4 v215, v[166:169], s[34:35] offset:256
	v_mov_b32_e32 v216, v248
	v_pk_mul_f32 v[114:115], v[114:115], v[216:217] op_sel_hi:[1,0]
	v_pk_mul_f32 v[116:117], v[116:117], v[216:217] op_sel_hi:[1,0]
	v_pk_mul_f32 v[106:107], v[106:107], v[216:217] op_sel_hi:[1,0]
	v_pk_mul_f32 v[108:109], v[108:109], v[216:217] op_sel_hi:[1,0]
	v_pk_mul_f32 v[102:103], v[102:103], v[216:217] op_sel_hi:[1,0]
	v_pk_mul_f32 v[104:105], v[104:105], v[216:217] op_sel_hi:[1,0]
	v_pk_mul_f32 v[98:99], v[98:99], v[216:217] op_sel_hi:[1,0]
	v_pk_mul_f32 v[100:101], v[100:101], v[216:217] op_sel_hi:[1,0]
	v_pk_fma_f32 v[114:115], v[114:115], v[178:179], v[146:147]
	v_pk_fma_f32 v[116:117], v[116:117], v[180:181], v[148:149]
	v_pk_fma_f32 v[106:107], v[106:107], v[182:183], v[150:151]
	v_pk_fma_f32 v[108:109], v[108:109], v[184:185], v[152:153]
	v_pk_fma_f32 v[102:103], v[102:103], v[186:187], v[154:155]
	v_pk_fma_f32 v[104:105], v[104:105], v[188:189], v[156:157]
	v_pk_fma_f32 v[98:99], v[98:99], v[190:191], v[158:159]
	v_pk_fma_f32 v[100:101], v[100:101], v[192:193], v[160:161]
	s_add_u32 s34, s22, 0x8000
	s_addc_u32 s35, s23, 0
	v_cvt_pk_bf16_f32 v170, v114, v115
	v_cvt_pk_bf16_f32 v171, v116, v117
	v_cvt_pk_bf16_f32 v172, v106, v107
	v_cvt_pk_bf16_f32 v173, v108, v109
	global_store_dwordx4 v215, v[170:173], s[34:35]
	v_cvt_pk_bf16_f32 v174, v102, v103
	v_cvt_pk_bf16_f32 v175, v104, v105
	v_cvt_pk_bf16_f32 v176, v98, v99
	v_cvt_pk_bf16_f32 v177, v100, v101
	global_store_dwordx4 v215, v[174:177], s[34:35] offset:256
	v_mov_b32_e32 v216, v249
	v_pk_mul_f32 v[94:95], v[94:95], v[216:217] op_sel_hi:[1,0]
	v_pk_mul_f32 v[96:97], v[96:97], v[216:217] op_sel_hi:[1,0]
	v_pk_mul_f32 v[90:91], v[90:91], v[216:217] op_sel_hi:[1,0]
	v_pk_mul_f32 v[92:93], v[92:93], v[216:217] op_sel_hi:[1,0]
	v_pk_mul_f32 v[86:87], v[86:87], v[216:217] op_sel_hi:[1,0]
	v_pk_mul_f32 v[88:89], v[88:89], v[216:217] op_sel_hi:[1,0]
	v_pk_mul_f32 v[82:83], v[82:83], v[216:217] op_sel_hi:[1,0]
	v_pk_mul_f32 v[84:85], v[84:85], v[216:217] op_sel_hi:[1,0]
	v_pk_fma_f32 v[94:95], v[94:95], v[178:179], v[146:147]
	v_pk_fma_f32 v[96:97], v[96:97], v[180:181], v[148:149]
	v_pk_fma_f32 v[90:91], v[90:91], v[182:183], v[150:151]
	v_pk_fma_f32 v[92:93], v[92:93], v[184:185], v[152:153]
	v_pk_fma_f32 v[86:87], v[86:87], v[186:187], v[154:155]
	v_pk_fma_f32 v[88:89], v[88:89], v[188:189], v[156:157]
	v_pk_fma_f32 v[82:83], v[82:83], v[190:191], v[158:159]
	v_pk_fma_f32 v[84:85], v[84:85], v[192:193], v[160:161]
	s_add_u32 s34, s22, 0x10000
	s_addc_u32 s35, s23, 0
	v_cvt_pk_bf16_f32 v162, v94, v95
	v_cvt_pk_bf16_f32 v163, v96, v97
	v_cvt_pk_bf16_f32 v164, v90, v91
	v_cvt_pk_bf16_f32 v165, v92, v93
	global_store_dwordx4 v215, v[162:165], s[34:35]
	v_cvt_pk_bf16_f32 v166, v86, v87
	v_cvt_pk_bf16_f32 v167, v88, v89
	v_cvt_pk_bf16_f32 v168, v82, v83
	v_cvt_pk_bf16_f32 v169, v84, v85
	global_store_dwordx4 v215, v[166:169], s[34:35] offset:256
	v_mov_b32_e32 v216, v250
	v_pk_mul_f32 v[78:79], v[78:79], v[216:217] op_sel_hi:[1,0]
	v_pk_mul_f32 v[80:81], v[80:81], v[216:217] op_sel_hi:[1,0]
	v_pk_mul_f32 v[74:75], v[74:75], v[216:217] op_sel_hi:[1,0]
	v_pk_mul_f32 v[76:77], v[76:77], v[216:217] op_sel_hi:[1,0]
	v_pk_mul_f32 v[70:71], v[70:71], v[216:217] op_sel_hi:[1,0]
	v_pk_mul_f32 v[72:73], v[72:73], v[216:217] op_sel_hi:[1,0]
	v_pk_mul_f32 v[66:67], v[66:67], v[216:217] op_sel_hi:[1,0]
	v_pk_mul_f32 v[68:69], v[68:69], v[216:217] op_sel_hi:[1,0]
	v_pk_fma_f32 v[78:79], v[78:79], v[178:179], v[146:147]
	v_pk_fma_f32 v[80:81], v[80:81], v[180:181], v[148:149]
	v_pk_fma_f32 v[74:75], v[74:75], v[182:183], v[150:151]
	v_pk_fma_f32 v[76:77], v[76:77], v[184:185], v[152:153]
	v_pk_fma_f32 v[70:71], v[70:71], v[186:187], v[154:155]
	v_pk_fma_f32 v[72:73], v[72:73], v[188:189], v[156:157]
	v_pk_fma_f32 v[66:67], v[66:67], v[190:191], v[158:159]
	v_pk_fma_f32 v[68:69], v[68:69], v[192:193], v[160:161]
	s_add_u32 s34, s22, 0x18000
	s_addc_u32 s35, s23, 0
	v_cvt_pk_bf16_f32 v170, v78, v79
	v_cvt_pk_bf16_f32 v171, v80, v81
	v_cvt_pk_bf16_f32 v172, v74, v75
	v_cvt_pk_bf16_f32 v173, v76, v77
	global_store_dwordx4 v215, v[170:173], s[34:35]
	v_cvt_pk_bf16_f32 v174, v70, v71
	v_cvt_pk_bf16_f32 v175, v72, v73
	v_cvt_pk_bf16_f32 v176, v66, v67
	v_cvt_pk_bf16_f32 v177, v68, v69
	global_store_dwordx4 v215, v[174:177], s[34:35] offset:256
	v_mov_b32_e32 v216, v251
	v_pk_mul_f32 v[62:63], v[62:63], v[216:217] op_sel_hi:[1,0]
	v_pk_mul_f32 v[64:65], v[64:65], v[216:217] op_sel_hi:[1,0]
	v_pk_mul_f32 v[58:59], v[58:59], v[216:217] op_sel_hi:[1,0]
	v_pk_mul_f32 v[60:61], v[60:61], v[216:217] op_sel_hi:[1,0]
	v_pk_mul_f32 v[54:55], v[54:55], v[216:217] op_sel_hi:[1,0]
	v_pk_mul_f32 v[56:57], v[56:57], v[216:217] op_sel_hi:[1,0]
	v_pk_mul_f32 v[50:51], v[50:51], v[216:217] op_sel_hi:[1,0]
	v_pk_mul_f32 v[52:53], v[52:53], v[216:217] op_sel_hi:[1,0]
	v_pk_fma_f32 v[62:63], v[62:63], v[178:179], v[146:147]
	v_pk_fma_f32 v[64:65], v[64:65], v[180:181], v[148:149]
	v_pk_fma_f32 v[58:59], v[58:59], v[182:183], v[150:151]
	v_pk_fma_f32 v[60:61], v[60:61], v[184:185], v[152:153]
	v_pk_fma_f32 v[54:55], v[54:55], v[186:187], v[154:155]
	v_pk_fma_f32 v[56:57], v[56:57], v[188:189], v[156:157]
	v_pk_fma_f32 v[50:51], v[50:51], v[190:191], v[158:159]
	v_pk_fma_f32 v[52:53], v[52:53], v[192:193], v[160:161]
	s_add_u32 s34, s22, 0x40000
	s_addc_u32 s35, s23, 0
	v_cvt_pk_bf16_f32 v162, v62, v63
	v_cvt_pk_bf16_f32 v163, v64, v65
	v_cvt_pk_bf16_f32 v164, v58, v59
	v_cvt_pk_bf16_f32 v165, v60, v61
	global_store_dwordx4 v215, v[162:165], s[34:35]
	v_cvt_pk_bf16_f32 v166, v54, v55
	v_cvt_pk_bf16_f32 v167, v56, v57
	v_cvt_pk_bf16_f32 v168, v50, v51
	v_cvt_pk_bf16_f32 v169, v52, v53
	global_store_dwordx4 v215, v[166:169], s[34:35] offset:256
	v_mov_b32_e32 v216, v252
	v_pk_mul_f32 v[46:47], v[46:47], v[216:217] op_sel_hi:[1,0]
	v_pk_mul_f32 v[48:49], v[48:49], v[216:217] op_sel_hi:[1,0]
	v_pk_mul_f32 v[42:43], v[42:43], v[216:217] op_sel_hi:[1,0]
	v_pk_mul_f32 v[44:45], v[44:45], v[216:217] op_sel_hi:[1,0]
	v_pk_mul_f32 v[38:39], v[38:39], v[216:217] op_sel_hi:[1,0]
	v_pk_mul_f32 v[40:41], v[40:41], v[216:217] op_sel_hi:[1,0]
	v_pk_mul_f32 v[34:35], v[34:35], v[216:217] op_sel_hi:[1,0]
	v_pk_mul_f32 v[36:37], v[36:37], v[216:217] op_sel_hi:[1,0]
	v_pk_fma_f32 v[46:47], v[46:47], v[178:179], v[146:147]
	v_pk_fma_f32 v[48:49], v[48:49], v[180:181], v[148:149]
	v_pk_fma_f32 v[42:43], v[42:43], v[182:183], v[150:151]
	v_pk_fma_f32 v[44:45], v[44:45], v[184:185], v[152:153]
	v_pk_fma_f32 v[38:39], v[38:39], v[186:187], v[154:155]
	v_pk_fma_f32 v[40:41], v[40:41], v[188:189], v[156:157]
	v_pk_fma_f32 v[34:35], v[34:35], v[190:191], v[158:159]
	v_pk_fma_f32 v[36:37], v[36:37], v[192:193], v[160:161]
	s_add_u32 s34, s22, 0x48000
	s_addc_u32 s35, s23, 0
	v_cvt_pk_bf16_f32 v170, v46, v47
	v_cvt_pk_bf16_f32 v171, v48, v49
	v_cvt_pk_bf16_f32 v172, v42, v43
	v_cvt_pk_bf16_f32 v173, v44, v45
	global_store_dwordx4 v215, v[170:173], s[34:35]
	v_cvt_pk_bf16_f32 v174, v38, v39
	v_cvt_pk_bf16_f32 v175, v40, v41
	v_cvt_pk_bf16_f32 v176, v34, v35
	v_cvt_pk_bf16_f32 v177, v36, v37
	global_store_dwordx4 v215, v[174:177], s[34:35] offset:256
	v_mov_b32_e32 v216, v253
	v_pk_mul_f32 v[30:31], v[30:31], v[216:217] op_sel_hi:[1,0]
	v_pk_mul_f32 v[32:33], v[32:33], v[216:217] op_sel_hi:[1,0]
	v_pk_mul_f32 v[26:27], v[26:27], v[216:217] op_sel_hi:[1,0]
	v_pk_mul_f32 v[28:29], v[28:29], v[216:217] op_sel_hi:[1,0]
	v_pk_mul_f32 v[22:23], v[22:23], v[216:217] op_sel_hi:[1,0]
	v_pk_mul_f32 v[24:25], v[24:25], v[216:217] op_sel_hi:[1,0]
	v_pk_mul_f32 v[18:19], v[18:19], v[216:217] op_sel_hi:[1,0]
	v_pk_mul_f32 v[20:21], v[20:21], v[216:217] op_sel_hi:[1,0]
	v_pk_fma_f32 v[30:31], v[30:31], v[178:179], v[146:147]
	v_pk_fma_f32 v[32:33], v[32:33], v[180:181], v[148:149]
	v_pk_fma_f32 v[26:27], v[26:27], v[182:183], v[150:151]
	v_pk_fma_f32 v[28:29], v[28:29], v[184:185], v[152:153]
	v_pk_fma_f32 v[22:23], v[22:23], v[186:187], v[154:155]
	v_pk_fma_f32 v[24:25], v[24:25], v[188:189], v[156:157]
	v_pk_fma_f32 v[18:19], v[18:19], v[190:191], v[158:159]
	v_pk_fma_f32 v[20:21], v[20:21], v[192:193], v[160:161]
	s_add_u32 s34, s22, 0x50000
	s_addc_u32 s35, s23, 0
	v_cvt_pk_bf16_f32 v162, v30, v31
	v_cvt_pk_bf16_f32 v163, v32, v33
	v_cvt_pk_bf16_f32 v164, v26, v27
	v_cvt_pk_bf16_f32 v165, v28, v29
	global_store_dwordx4 v215, v[162:165], s[34:35]
	v_cvt_pk_bf16_f32 v166, v22, v23
	v_cvt_pk_bf16_f32 v167, v24, v25
	v_cvt_pk_bf16_f32 v168, v18, v19
	v_cvt_pk_bf16_f32 v169, v20, v21
	global_store_dwordx4 v215, v[166:169], s[34:35] offset:256
	v_mov_b32_e32 v216, v254
	v_pk_mul_f32 v[14:15], v[14:15], v[216:217] op_sel_hi:[1,0]
	v_pk_mul_f32 v[16:17], v[16:17], v[216:217] op_sel_hi:[1,0]
	v_pk_mul_f32 v[10:11], v[10:11], v[216:217] op_sel_hi:[1,0]
	v_pk_mul_f32 v[12:13], v[12:13], v[216:217] op_sel_hi:[1,0]
	v_pk_mul_f32 v[6:7], v[6:7], v[216:217] op_sel_hi:[1,0]
	v_pk_mul_f32 v[8:9], v[8:9], v[216:217] op_sel_hi:[1,0]
	v_pk_mul_f32 v[2:3], v[2:3], v[216:217] op_sel_hi:[1,0]
	v_pk_mul_f32 v[4:5], v[4:5], v[216:217] op_sel_hi:[1,0]
	v_pk_fma_f32 v[14:15], v[14:15], v[178:179], v[146:147]
	v_pk_fma_f32 v[16:17], v[16:17], v[180:181], v[148:149]
	v_pk_fma_f32 v[10:11], v[10:11], v[182:183], v[150:151]
	v_pk_fma_f32 v[12:13], v[12:13], v[184:185], v[152:153]
	v_pk_fma_f32 v[6:7], v[6:7], v[186:187], v[154:155]
	v_pk_fma_f32 v[8:9], v[8:9], v[188:189], v[156:157]
	v_pk_fma_f32 v[2:3], v[2:3], v[190:191], v[158:159]
	v_pk_fma_f32 v[4:5], v[4:5], v[192:193], v[160:161]
	s_add_u32 s34, s22, 0x58000
	s_addc_u32 s35, s23, 0
	v_cvt_pk_bf16_f32 v170, v14, v15
	v_cvt_pk_bf16_f32 v171, v16, v17
	v_cvt_pk_bf16_f32 v172, v10, v11
	v_cvt_pk_bf16_f32 v173, v12, v13
	global_store_dwordx4 v215, v[170:173], s[34:35]
	v_cvt_pk_bf16_f32 v174, v6, v7
	v_cvt_pk_bf16_f32 v175, v8, v9
	v_cvt_pk_bf16_f32 v176, v2, v3
	v_cvt_pk_bf16_f32 v177, v4, v5
	global_store_dwordx4 v215, v[174:177], s[34:35] offset:256
